# GEMM K-loop: static s_setprio 1 for the older wave half (waves 0-3) instead of the younger
# speedup vs baseline: 1.0017x; 1.0017x over previous
; #define PG8_STAGE(bufoff, gbase, voff) do { _Pragma("unroll") for (int _i = 0; _i < 2; ++_i) \
;         __builtin_amdgcn_global_load_lds((const unsigned*)((const char*)(gbase) + (voff)[_i]), (LAS unsigned*)(lds + (bufoff) + ldsw + _i * 8192), 16, 0, 0); } while (0)
; #define PG8_WAIT_V(n) asm volatile("s_waitcnt vmcnt(" #n ")" ::: "memory")
; #define PG8_BAR __builtin_amdgcn_s_barrier()
; template <class Epi>
; __device__ __forceinline__ void gemm_phase(LAS unsigned char* lds, const Gemm g, const StaticOrder& S, const Epi& E) {
;     int tid_ = threadIdx.x; asm volatile("" : "+v"(tid_));
;     const int tid = tid_, wid = __builtin_amdgcn_readfirstlane(tid >> 6), lane = tid & 63, wr = wid >> 2, wc = wid & 3, fr = lane & 15, fq = lane >> 4;
;     const int K = g.K, nt = K / BK, npass = g.A2 ? 2 : 1;
;     unsigned voffA[2], voffB[2];
; #pragma unroll
;     for (int i = 0; i < 2; ++i) { int R, C; stage_rc(tid * 16 + i * 8192, R, C); const int Rb = Epi::PERM ? ((R & ~31) + perm32(R & 31)) : R;
;         voffA[i] = (unsigned)(R * g.lda + C) * 2u; voffB[i] = (unsigned)(Rb * g.ldb + C) * 2u; }
;     const size_t kstep = (size_t)(BK * 2);
;     const size_t hstepA = (size_t)HALF * g.lda * 2, hstepB = (size_t)HALF * g.ldb * 2;
;     const size_t tstepA = 2 * hstepA, tstepB = 2 * hstepB;
;     const unsigned ldsw = (unsigned)wid * 1024u;
;     const int aoff = lds_byte(wr * 64 + fr, fq * 8), boff = lds_byte(wc * 32 + fr, fq * 8);
;     ...
;     Unit cur, nxt; int ui = 0;
;     if (!S.next(0, cur)) return;
;     f32x4 acc[2][2][4][2];
; #pragma unroll
;     for (int a = 0; a < 2; ++a)
; #pragma unroll
;         for (int b = 0; b < 2; ++b)
; #pragma unroll
;             for (int m = 0; m < 4; ++m)
; #pragma unroll
;                 for (int n = 0; n < 2; ++n) acc[a][b][m][n] = (f32x4){0.f, 0.f, 0.f, 0.f};
;     bf16x8 At[4][2], B0[2][2], B1[2][2];
;     const char* cA = (const char*)g.A + (size_t)cur.pm * tstepA; const char* cB = (const char*)g.Bt + (size_t)cur.pn * tstepB;
;     PG8_STAGE(PG8_SB(0, 0), cB, voffB); PG8_STAGE(PG8_SA(0, 0), cA, voffA); PG8_STAGE(PG8_SB(0, 1), cB + hstepB, voffB); PG8_STAGE(PG8_SA(0, 1), cA + hstepA, voffA);
;     if (wr == 1) PG8_BAR;
;     PG8_WAIT_V(4); PG8_BAR;
;     PG8_STAGE(PG8_SB(1, 0), cB + kstep, voffB); PG8_STAGE(PG8_SA(1, 0), cA + kstep, voffA); PG8_STAGE(PG8_SB(1, 1), cB + hstepB + kstep, voffB);
.LBB0_291:
	s_andn2_b64 vcc, exec, s[0:1]
	s_cbranch_vccnz .LBB0_587
	v_bfe_i32 v2, v11, 27, 1
	v_lshlrev_b32_e32 v0, 4, v11
	v_lshrrev_b32_e32 v2, 22, v2
	v_add_u32_e32 v2, v0, v2
	v_and_b32_e32 v2, 0xfffffc00, v2
	v_sub_u32_e32 v2, v0, v2
	v_ashrrev_i32_e32 v1, 31, v11
	v_lshrrev_b32_e32 v3, 4, v2
	v_lshrrev_b32_e32 v1, 26, v1
	v_bitop3_b32 v2, v3, v2, 32 bitop3:0x6c
	v_add_u32_e32 v1, v11, v1
	v_ashrrev_i32_e32 v4, 31, v2
	v_ashrrev_i32_e32 v1, 6, v1
	v_lshrrev_b32_e32 v4, 26, v4
	v_lshlrev_b32_e32 v3, 3, v1
	v_add_u32_e32 v4, v2, v4
	v_lshlrev_b32_e32 v1, 5, v1
	v_and_b32_e32 v9, 32, v1
	v_and_b32_e32 v1, 0xc0, v4
	v_and_b32_e32 v3, -16, v3
	v_ashrrev_i32_e32 v5, 6, v4
	v_sub_u32_e32 v1, v2, v1
	v_mov_b32_e32 v6, 1
	v_add_u32_e32 v3, v5, v3
	v_ashrrev_i16_sdwa v1, v6, sext(v1) dst_sel:DWORD dst_unused:UNUSED_PAD src0_sel:DWORD src1_sel:BYTE_0
	v_bfe_i32 v10, v1, 0, 16
	v_lshlrev_b32_e32 v2, 1, v3
	v_lshrrev_b32_e32 v4, 2, v3
	v_and_b32_e32 v5, 3, v5
	s_mov_b32 s1, 0x1fffe0
	v_add_u32_e32 v1, v9, v10
	v_and_b32_e32 v2, 24, v2
	v_and_b32_e32 v4, 4, v4
	v_and_or_b32 v5, v3, s1, v5
	v_mul_lo_u32 v12, v3, s4
	v_or3_b32 v2, v5, v4, v2
	v_add_lshl_u32 v180, v1, v12, 1
	v_lshlrev_b32_e32 v1, 1, v1
	v_add_u32_e32 v0, 0x2000, v0
	v_lshl_add_u32 v182, v2, 11, v1
	v_ashrrev_i32_e32 v1, 31, v0
	v_lshrrev_b32_e32 v1, 22, v1
	v_add_u32_e32 v1, v0, v1
	v_ashrrev_i32_e32 v1, 10, v1
	v_mul_i32_i24_e32 v2, 0x400, v1
	v_sub_u32_e32 v0, v0, v2
	v_lshrrev_b32_e32 v2, 4, v0
	v_bitop3_b32 v0, v2, v0, 32 bitop3:0x6c
	v_ashrrev_i32_e32 v3, 31, v0
	v_lshrrev_b32_e32 v3, 26, v3
	v_lshlrev_b32_e32 v2, 3, v1
	v_add_u32_e32 v3, v0, v3
	v_and_b32_e32 v2, -16, v2
	v_ashrrev_i32_e32 v4, 6, v3
	v_readlane_b32 s6, v255, 42
	v_add_u32_e32 v2, v4, v2
	v_lshlrev_b32_e32 v1, 5, v1
	v_and_b32_e32 v4, 3, v4
	v_and_b32_e32 v13, 32, v1
	v_and_b32_e32 v1, 0xc0, v3
	v_and_or_b32 v4, v2, s1, v4
	s_ashr_i32 s1, s6, 6
	s_ashr_i32 s53, s52, 31
	s_ashr_i32 s0, s6, 8
	v_sub_u32_e32 v0, v0, v1
	s_lshl_b32 s54, s4, 8
	s_lshl_b32 s56, s4, 9
	s_lshl_b32 s57, s1, 10
	s_lshl_b64 s[8:9], s[52:53], 19
	v_readlane_b32 s10, v255, 29
	v_ashrrev_i16_sdwa v0, v6, sext(v0) dst_sel:DWORD dst_unused:UNUSED_PAD src0_sel:DWORD src1_sel:BYTE_0
	v_readlane_b32 s11, v255, 30
	s_add_u32 s58, s10, s8
	v_bfe_i32 v14, v0, 0, 16
	v_lshlrev_b32_e32 v1, 1, v2
	v_lshrrev_b32_e32 v3, 2, v2
	s_addc_u32 s59, s11, s9
	s_add_i32 s12, s57, 0
	v_add_u32_e32 v0, v13, v14
	v_and_b32_e32 v1, 24, v1
	v_and_b32_e32 v3, 4, v3
	v_mul_lo_u32 v15, v2, s4
	s_add_i32 m0, s12, 0x10000
	v_or3_b32 v1, v4, v3, v1
	v_add_lshl_u32 v184, v0, v15, 1
	v_lshlrev_b32_e32 v0, 1, v0
	s_mul_i32 s6, s56, s73
	global_load_lds_dwordx4 v182, s[58:59]
	s_add_i32 m0, s12, 0x12000
	v_readlane_b32 s8, v255, 39
	v_lshl_add_u32 v186, v1, 11, v0
	s_mul_hi_i32 s4, s56, s73
	v_readlane_b32 s9, v255, 40
	s_add_u32 s60, s8, s6
	global_load_lds_dwordx4 v186, s[58:59]
	s_addc_u32 s61, s9, s4
	s_mov_b32 m0, s12
	s_add_i32 s13, s12, 0x2000
	global_load_lds_dwordx4 v180, s[60:61]
	s_mov_b32 m0, s13
	s_add_u32 s8, s58, 0x40000
	global_load_lds_dwordx4 v184, s[60:61]
	s_addc_u32 s9, s59, 0
	s_add_i32 m0, s12, 0x14000
	v_mov_b32_e32 v183, v177
	global_load_lds_dwordx4 v182, s[8:9]
	s_add_i32 m0, s12, 0x16000
	v_mov_b32_e32 v187, v177
	global_load_lds_dwordx4 v186, s[8:9]
	s_add_u32 s8, s60, s54
	s_addc_u32 s9, s61, 0
	s_add_i32 s4, s12, 0x4000
	s_mov_b32 m0, s4
	s_add_i32 s70, s12, 0x6000
	global_load_lds_dwordx4 v180, s[8:9]
	s_mov_b32 m0, s70
	v_mov_b32_e32 v181, v177
	global_load_lds_dwordx4 v184, s[8:9]
	v_mov_b32_e32 v185, v177
	s_mov_b32 s55, s37
	v_lshl_add_u64 v[6:7], s[58:59], 0, v[182:183]
	v_lshl_add_u64 v[4:5], s[58:59], 0, v[186:187]
	v_lshl_add_u64 v[2:3], s[60:61], 0, v[180:181]
	s_cmp_lg_u32 s0, 1
	v_lshl_add_u64 v[0:1], s[60:61], 0, v[184:185]
	s_mov_b32 s24, 0x3db504f3
	s_setprio 1
	s_cbranch_scc1 .LBB0_294
	s_barrier
	s_setprio 0
